# attention: no-running-max path from the first tile of every item (vote catches row sums outside 2^-100..2^100 and reruns the item with the exact running-max loop)
# baseline (speedup 1.0000x reference)
.LBB0_879:
	s_mul_i32 s9, s54, s30
	s_cmpk_gt_i32 s9, 0x7ff
	s_mov_b32 s14, 5
	s_cbranch_scc1 .LBB0_894
	s_bitcmp0_b32 s54, 0
	s_cselect_b32 s8, s2, s17
	s_add_i32 s9, s8, s9
	s_cmpk_gt_i32 s9, 0x7ff
	s_mov_b32 s14, 7
	s_cbranch_scc1 .LBB0_894
	s_ashr_i32 s12, s9, 6
	s_and_b32 s15, s9, 7
	s_lshr_b32 s9, s9, 2
	s_sub_i32 s14, 31, s12
	s_and_b32 s9, s9, 14
	v_add_u32_e32 v206, s9, v200
	s_lshl_b32 s9, s15, 12
	s_lshl_b32 s55, s14, 7
	s_add_i32 s55, s55, s9
	s_lshr_b32 s9, s55, 8
	s_and_b32 s9, s9, 0xfffff0
	v_add_u32_e32 v172, s9, v206
	s_lshl_b32 s9, s14, 2
	v_lshlrev_b32_e32 v1, 7, v172
	s_and_b32 s9, s9, 0x7c
	v_or3_b32 v1, v1, s9, v201
	v_mad_i64_i32 v[2:3], s[12:13], v1, s36, v[162:163]
	v_add_co_u32_e32 v4, vcc, s37, v2
	global_load_dwordx4 v[98:101], v[2:3], off
	global_load_dwordx4 v[102:105], v[2:3], off offset:1024
	global_load_dwordx4 v[106:109], v[2:3], off offset:2048
	global_load_dwordx4 v[110:113], v[2:3], off offset:3072
	v_addc_co_u32_e32 v5, vcc, 0, v3, vcc
	v_add_co_u32_e32 v2, vcc, s40, v2
	s_lshl_b32 s56, s14, 1
	s_nop 0
	v_addc_co_u32_e32 v3, vcc, 0, v3, vcc
	global_load_dwordx4 v[114:117], v[4:5], off offset:1024
	global_load_dwordx4 v[118:121], v[4:5], off offset:2048
	global_load_dwordx4 v[122:125], v[2:3], off offset:-4096
	global_load_dwordx4 v[126:129], v[4:5], off offset:3072
	global_load_dwordx4 v[130:133], v[2:3], off
	global_load_dwordx4 v[134:137], v[2:3], off offset:1024
	global_load_dwordx4 v[138:141], v[2:3], off offset:2048
	global_load_dwordx4 v[142:145], v[2:3], off offset:3072
	s_mul_i32 s15, s15, 0x180000
	s_add_u32 s12, s42, s15
	s_addc_u32 s13, s43, 0
	v_readfirstlane_b32 s9, v203
	v_lshl_add_u64 v[2:3], s[12:13], 0, v[164:165]
	s_mov_b32 m0, s9
	v_readfirstlane_b32 s9, v204
	global_load_lds_dwordx4 v[2:3], off
	v_lshl_add_u64 v[2:3], s[12:13], 0, v[166:167]
	s_mov_b32 m0, s9
	v_readfirstlane_b32 s9, v205
	global_load_lds_dwordx4 v[2:3], off
	v_lshl_add_u64 v[2:3], s[12:13], 0, v[168:169]
	s_mov_b32 m0, s9
	s_add_i32 s8, s3, s8
	global_load_lds_dwordx4 v[2:3], off
	s_and_b32 s8, s8, 7
	v_mov_b32_e32 v14, v0
	v_mov_b32_e32 v15, v0
	s_mul_i32 s8, s8, 0x180000
	v_mov_b32_e32 v1, v0
	v_mov_b32_e32 v2, v0
	v_mov_b32_e32 v3, v0
	v_mov_b32_e32 v4, v0
	v_mov_b32_e32 v5, v0
	v_mov_b32_e32 v6, v0
	v_mov_b32_e32 v7, v0
	v_mov_b32_e32 v8, v0
	v_mov_b32_e32 v9, v0
	v_mov_b32_e32 v10, v0
	v_mov_b32_e32 v11, v0
	v_mov_b32_e32 v12, v0
	v_mov_b32_e32 v13, v0
	v_mov_b64_e32 v[64:65], v[14:15]
	v_mov_b64_e32 v[48:49], v[14:15]
	v_mov_b64_e32 v[32:33], v[14:15]
	s_add_u32 s8, s28, s8
	v_mov_b64_e32 v[62:63], v[12:13]
	v_mov_b64_e32 v[60:61], v[10:11]
	v_mov_b64_e32 v[58:59], v[8:9]
	v_mov_b64_e32 v[56:57], v[6:7]
	v_mov_b64_e32 v[54:55], v[4:5]
	v_mov_b64_e32 v[52:53], v[2:3]
	v_mov_b64_e32 v[50:51], v[0:1]
	v_mov_b64_e32 v[46:47], v[12:13]
	v_mov_b64_e32 v[44:45], v[10:11]
	v_mov_b64_e32 v[42:43], v[8:9]
	v_mov_b64_e32 v[40:41], v[6:7]
	v_mov_b64_e32 v[38:39], v[4:5]
	v_mov_b64_e32 v[36:37], v[2:3]
	v_mov_b64_e32 v[34:35], v[0:1]
	v_mov_b64_e32 v[30:31], v[12:13]
	v_mov_b64_e32 v[28:29], v[10:11]
	v_mov_b64_e32 v[26:27], v[8:9]
	v_mov_b64_e32 v[24:25], v[6:7]
	v_mov_b64_e32 v[22:23], v[4:5]
	v_mov_b64_e32 v[20:21], v[2:3]
	v_mov_b64_e32 v[18:19], v[0:1]
	v_mov_b64_e32 v[16:17], v[14:15]
	s_mov_b32 s57, 0
	s_addc_u32 s9, s29, 0
	v_mov_b64_e32 v[210:211], 0
	v_mov_b64_e32 v[212:213], 0
	v_mov_b64_e32 v[214:215], 0
	v_mov_b64_e32 v[216:217], 0
	v_mov_b64_e32 v[218:219], 0
	v_mov_b64_e32 v[220:221], 0
	v_mov_b64_e32 v[222:223], 0
	v_mov_b64_e32 v[224:225], 0
	v_mov_b32_e32 v173, 0
	v_mov_b64_e32 v[14:15], v[12:13]
	v_mov_b64_e32 v[12:13], v[10:11]
	v_mov_b64_e32 v[10:11], v[8:9]
	v_mov_b64_e32 v[8:9], v[6:7]
	v_mov_b64_e32 v[6:7], v[4:5]
	v_mov_b64_e32 v[4:5], v[2:3]
	v_mov_b64_e32 v[2:3], v[0:1]
	s_or_b32 s75, s56, s76
	s_waitcnt vmcnt(0) lgkmcnt(0)
	s_barrier
	s_cmp_eq_u32 s78, 0
	s_cbranch_scc1 .Lu884
	s_branch .LBB0_884

.LBB0_893:
	s_cmp_lg_u32 s78, 0
	s_cbranch_scc1 .Lopt_done
	v_cmp_ngt_f32_e32 vcc, 0x71800000, v173
	s_mov_b64 s[100:101], vcc
	v_cmp_nlt_f32_e32 vcc, 0x0d800000, v173
	s_or_b64 vcc, vcc, s[100:101]
	s_cmp_eq_u64 vcc, 0
	s_cbranch_scc1 .Lopt_vote
	v_mov_b32_e32 v1, 0x23ff8
	v_mov_b32_e32 v180, 1
	ds_write_b32 v1, v180
